# v8 (pointer-based K/V tile loads in fast attention loops) plus a second s_barrier after each attention tile barrier
# speedup vs baseline: 1.0851x; 1.0116x over previous
.LBB0_159:
	s_or_b64 exec, exec, s[14:15]
	global_load_dwordx4 v[124:127], v[10:11], off offset:128
	s_movk_i32 s6, 0xd0
	v_mul_lo_u32 v9, v12, s6
	v_lshl_add_u32 v157, v6, 4, v9
	v_mul_lo_u32 v6, v7, s6
	v_lshl_add_u32 v158, v8, 4, v6
	s_waitcnt vmcnt(3)
	ds_write_b128 v157, v[104:107]
	s_and_saveexec_b64 s[12:13], s[38:39]
	ds_write_b128 v158, v[112:115]
	s_or_b64 exec, exec, s[12:13]
	v_mad_i64_i32 v[6:7], s[12:13], v156, s54, 0
	s_and_b64 s[12:13], s[88:89], exec
	s_cselect_b32 s14, 0x84, 4
	v_lshl_add_u64 v[6:7], s[2:3], 0, v[6:7]
	s_add_u32 s2, s52, s96
	v_lshl_add_u64 v[6:7], v[6:7], 0, v[0:1]
	s_addc_u32 s3, s53, 0
	v_lshl_add_u64 v[150:151], s[2:3], 0, v[6:7]
	s_add_u32 s2, s40, s41
	v_and_b32_e32 v8, 31, v148
	s_addc_u32 s3, s23, 0
	v_mul_u32_u24_e32 v16, 0xd0, v8
	v_lshlrev_b32_e32 v8, 6, v8
	v_cmp_lt_i32_e32 vcc, v207, v206
	s_add_u32 s2, s52, s2
	v_mul_lo_u32 v9, v156, s4
	v_sub_u32_e32 v17, v16, v8
	v_cndmask_b32_e32 v8, v205, v207, vcc
	s_addc_u32 s3, s53, s3
	v_mov_b32_e32 v14, v1
	v_mov_b32_e32 v15, v1
	v_lshl_add_u32 v160, v140, 4, v9
	v_lshlrev_b32_e32 v159, 2, v8
	v_lshl_add_u64 v[152:153], v[2:3], 1, s[2:3]
	v_lshl_add_u64 v[154:155], v[4:5], 1, s[2:3]
	v_mov_b32_e32 v0, v1
	v_mov_b32_e32 v2, v1
	v_mov_b32_e32 v3, v1
	v_mov_b32_e32 v4, v1
	v_mov_b32_e32 v5, v1
	v_mov_b32_e32 v6, v1
	v_mov_b32_e32 v7, v1
	v_mov_b32_e32 v8, v1
	v_mov_b32_e32 v9, v1
	v_mov_b32_e32 v10, v1
	v_mov_b32_e32 v11, v1
	v_mov_b32_e32 v12, v1
	v_mov_b32_e32 v13, v1
	v_add_u32_e32 v164, v16, v130
	v_add_u32_e32 v165, v17, v130
	v_mov_b64_e32 v[30:31], v[14:15]
	v_mov_b64_e32 v[46:47], v[14:15]
	s_mov_b32 s22, 0
	v_mov_b32_e32 v161, 0
	v_bfrev_b32_e32 v218, 1
	v_mov_b32_e32 v219, v218
	v_mov_b32_e32 v220, v218
	v_mov_b32_e32 v221, v218
	v_mov_b32_e32 v222, v218
	v_mov_b32_e32 v223, v218
	v_mov_b32_e32 v224, v218
	v_mov_b32_e32 v225, v218
	v_mov_b32_e32 v226, v218
	v_mov_b32_e32 v227, v218
	v_mov_b32_e32 v228, v218
	v_mov_b32_e32 v229, v218
	v_mov_b32_e32 v230, v218
	v_mov_b32_e32 v231, v218
	v_mov_b32_e32 v232, v218
	v_mov_b32_e32 v233, v218
	v_mov_b64_e32 v[28:29], v[12:13]
	v_mov_b64_e32 v[26:27], v[10:11]
	v_mov_b64_e32 v[24:25], v[8:9]
	v_mov_b64_e32 v[22:23], v[6:7]
	v_mov_b64_e32 v[20:21], v[4:5]
	v_mov_b64_e32 v[18:19], v[2:3]
	v_mov_b64_e32 v[16:17], v[0:1]
	v_mov_b64_e32 v[44:45], v[12:13]
	v_mov_b64_e32 v[42:43], v[10:11]
	v_mov_b64_e32 v[40:41], v[8:9]
	v_mov_b64_e32 v[38:39], v[6:7]
	v_mov_b64_e32 v[36:37], v[4:5]
	v_mov_b64_e32 v[34:35], v[2:3]
	v_mov_b64_e32 v[32:33], v[0:1]
	v_mov_b32_e32 v0, 0
	s_waitcnt vmcnt(2)
	ds_write_b128 v160, v[120:123] offset:13312
	s_waitcnt lgkmcnt(0)
	s_barrier
	s_cmp_lg_u32 s98, 0
	s_cbranch_scc1 .LBB0_162_sl
	v_lshl_add_u64 v[236:237], v[152:153], 0, s[20:21]
	v_lshl_add_u64 v[240:241], v[154:155], 0, s[20:21]
	v_lshl_add_u64 v[244:245], v[150:151], 0, s[20:21]
	s_mov_b32 s2, 0x9186800
	s_mov_b32 s3, 0
	v_lshl_add_u64 v[238:239], v[236:237], 0, s[2:3]
	v_lshl_add_u64 v[242:243], v[240:241], 0, s[2:3]
	s_mov_b32 s2, 0x9183800
	v_lshl_add_u64 v[236:237], v[236:237], 0, s[2:3]
	v_lshl_add_u64 v[240:241], v[240:241], 0, s[2:3]
	s_mov_b32 s2, 0xa40d900
	v_lshl_add_u64 v[244:245], v[244:245], 0, s[2:3]
.LBB0_162:
	s_add_i32 s15, s22, 2
	s_cmp_lt_u32 s15, s14
	s_cselect_b64 s[2:3], -1, 0
	s_cmp_ge_u32 s15, s14
	s_cselect_b64 s[90:91], -1, 0
	s_and_b64 vcc, exec, s[90:91]
	s_cbranch_vccnz .LBB0_166
	global_load_dwordx4 v[104:107], v[236:237], off
	s_and_saveexec_b64 s[12:13], s[38:39]
	s_cbranch_execz .LBB0_165
	global_load_dwordx4 v[112:115], v[240:241], off
.LBB0_165:
	s_or_b64 exec, exec, s[12:13]
	global_load_dwordx4 v[120:123], v[244:245], off

.LBB0_168:
	v_exp_f32_e32 v64, v64
	v_exp_f32_e32 v65, v65
	v_exp_f32_e32 v66, v66
	v_exp_f32_e32 v67, v67
	v_exp_f32_e32 v68, v68
	v_exp_f32_e32 v69, v69
	v_exp_f32_e32 v70, v70
	v_exp_f32_e32 v71, v71
	v_cvt_pk_bf16_f32 v166, v64, v65
	v_cvt_pk_bf16_f32 v167, v66, v67
	v_cvt_pk_bf16_f32 v168, v68, v69
	v_cvt_pk_bf16_f32 v169, v70, v71
	v_exp_f32_e32 v72, v72
	v_exp_f32_e32 v73, v73
	s_waitcnt lgkmcnt(0)
	v_mfma_f32_32x32x16_bf16 v[32:47], v[144:147], v[166:169], v[32:47]
	v_exp_f32_e32 v74, v74
	v_exp_f32_e32 v75, v75
	v_exp_f32_e32 v76, v76
	v_exp_f32_e32 v77, v77
	v_exp_f32_e32 v78, v78
	v_exp_f32_e32 v79, v79
	v_cvt_pk_bf16_f32 v170, v72, v73
	v_mfma_f32_32x32x16_bf16 v[16:31], v[128:131], v[166:169], v[16:31]
	v_cvt_pk_bf16_f32 v171, v74, v75
	v_cvt_pk_bf16_f32 v172, v76, v77
	v_cvt_pk_bf16_f32 v173, v78, v79
	v_exp_f32_e32 v48, v48
	v_exp_f32_e32 v49, v49
	v_exp_f32_e32 v50, v50
	v_exp_f32_e32 v51, v51
	v_mfma_f32_32x32x16_bf16 v[32:47], v[140:143], v[170:173], v[32:47]
	v_exp_f32_e32 v52, v52
	v_exp_f32_e32 v53, v53
	v_exp_f32_e32 v54, v54
	v_exp_f32_e32 v55, v55
	v_cvt_pk_bf16_f32 v174, v48, v49
	v_cvt_pk_bf16_f32 v175, v50, v51
	v_cvt_pk_bf16_f32 v176, v52, v53
	v_mfma_f32_32x32x16_bf16 v[16:31], v[10:13], v[170:173], v[16:31]
	v_cvt_pk_bf16_f32 v177, v54, v55
	v_exp_f32_e32 v56, v56
	v_exp_f32_e32 v57, v57
	v_exp_f32_e32 v58, v58
	v_exp_f32_e32 v59, v59
	v_exp_f32_e32 v60, v60
	v_exp_f32_e32 v61, v61
	v_mfma_f32_32x32x16_bf16 v[32:47], v[136:139], v[174:177], v[32:47]
	v_exp_f32_e32 v62, v62
	v_exp_f32_e32 v63, v63
	v_cvt_pk_bf16_f32 v178, v56, v57
	v_cvt_pk_bf16_f32 v179, v58, v59
	v_cvt_pk_bf16_f32 v180, v60, v61
	v_cvt_pk_bf16_f32 v181, v62, v63
	s_waitcnt vmcnt(1)
	ds_write_b128 v157, v[116:119] offset:22528
	v_mfma_f32_32x32x16_bf16 v[16:31], v[2:5], v[174:177], v[16:31]
	v_mfma_f32_32x32x16_bf16 v[32:47], v[132:135], v[178:181], v[32:47]
	v_mfma_f32_32x32x16_bf16 v[16:31], v[6:9], v[178:181], v[16:31]
	s_and_saveexec_b64 s[12:13], s[38:39]
	ds_write_b128 v158, v[108:111] offset:22528
	s_or_b64 exec, exec, s[12:13]
	s_add_i32 s12, s22, 3
	s_cmp_ge_u32 s12, s14
	s_waitcnt vmcnt(0)
	ds_write_b128 v160, v[124:127] offset:35840
	s_waitcnt lgkmcnt(0)
	s_barrier
	s_barrier
	s_cbranch_scc1 .LBB0_174
	global_load_dwordx4 v[116:119], v[238:239], off
	s_and_saveexec_b64 s[12:13], s[38:39]
	s_cbranch_execz .LBB0_173
	global_load_dwordx4 v[108:111], v[242:243], off
.LBB0_173:
	s_or_b64 exec, exec, s[12:13]
	global_load_dwordx4 v[124:127], v[244:245], off offset:128

.LBB0_180:
	v_add_f32_e32 v2, 0, v14
	v_add_f32_e32 v3, 0, v15
	v_add_f32_e32 v2, v2, v48
	v_add_f32_e32 v3, v3, v49
	v_add_f32_e32 v2, v64, v2
	v_add_f32_e32 v3, v50, v3
	v_add_f32_e32 v2, v65, v2
	v_add_f32_e32 v3, v51, v3
	v_add_f32_e32 v2, v66, v2
	v_add_f32_e32 v3, v52, v3
	v_add_f32_e32 v2, v67, v2
	v_add_f32_e32 v3, v53, v3
	v_add_f32_e32 v2, v68, v2
	v_add_f32_e32 v3, v54, v3
	v_add_f32_e32 v2, v69, v2
	v_add_f32_e32 v3, v55, v3
	v_add_f32_e32 v2, v70, v2
	v_add_f32_e32 v3, v56, v3
	v_add_f32_e32 v2, v71, v2
	v_add_f32_e32 v3, v57, v3
	v_add_f32_e32 v2, v72, v2
	v_add_f32_e32 v3, v58, v3
	v_add_f32_e32 v2, v73, v2
	v_add_f32_e32 v3, v59, v3
	v_add_f32_e32 v2, v74, v2
	v_add_f32_e32 v3, v60, v3
	v_add_f32_e32 v2, v75, v2
	v_add_f32_e32 v3, v61, v3
	v_add_f32_e32 v2, v76, v2
	v_add_f32_e32 v3, v62, v3
	v_add_f32_e32 v2, v77, v2
	v_add_f32_e32 v3, v63, v3
	v_add_f32_e32 v2, v3, v2
	v_add_f32_e32 v0, v0, v2
	v_lshl_add_u64 v[244:245], v[244:245], 0, s[30:31]
	v_lshl_add_u64 v[236:237], v[236:237], 0, s[26:27]
	v_lshl_add_u64 v[238:239], v[238:239], 0, s[26:27]
	s_andn2_b64 vcc, exec, s[90:91]
	v_lshl_add_u64 v[240:241], v[240:241], 0, s[26:27]
	v_lshl_add_u64 v[242:243], v[242:243], 0, s[26:27]
	s_waitcnt lgkmcnt(0)
	s_barrier
	s_barrier
	s_cbranch_vccz .LBB0_203
	s_mov_b32 s22, s15
	s_branch .LBB0_162

.LBB0_168_sl:
	v_exp_f32_e32 v64, v64
	v_exp_f32_e32 v65, v65
	v_exp_f32_e32 v66, v66
	v_exp_f32_e32 v67, v67
	v_exp_f32_e32 v68, v68
	v_exp_f32_e32 v69, v69
	v_exp_f32_e32 v70, v70
	v_exp_f32_e32 v71, v71
	v_cvt_pk_bf16_f32 v166, v64, v65
	v_cvt_pk_bf16_f32 v167, v66, v67
	v_cvt_pk_bf16_f32 v168, v68, v69
	v_cvt_pk_bf16_f32 v169, v70, v71
	v_exp_f32_e32 v72, v72
	v_exp_f32_e32 v73, v73
	s_waitcnt lgkmcnt(0)
	v_mfma_f32_32x32x16_bf16 v[32:47], v[144:147], v[166:169], v[32:47]
	v_exp_f32_e32 v74, v74
	v_exp_f32_e32 v75, v75
	v_exp_f32_e32 v76, v76
	v_exp_f32_e32 v77, v77
	v_exp_f32_e32 v78, v78
	v_exp_f32_e32 v79, v79
	v_cvt_pk_bf16_f32 v170, v72, v73
	v_mfma_f32_32x32x16_bf16 v[16:31], v[128:131], v[166:169], v[16:31]
	v_cvt_pk_bf16_f32 v171, v74, v75
	v_cvt_pk_bf16_f32 v172, v76, v77
	v_cvt_pk_bf16_f32 v173, v78, v79
	v_exp_f32_e32 v48, v48
	v_exp_f32_e32 v49, v49
	v_exp_f32_e32 v50, v50
	v_exp_f32_e32 v51, v51
	v_mfma_f32_32x32x16_bf16 v[32:47], v[140:143], v[170:173], v[32:47]
	v_exp_f32_e32 v52, v52
	v_exp_f32_e32 v53, v53
	v_exp_f32_e32 v54, v54
	v_exp_f32_e32 v55, v55
	v_cvt_pk_bf16_f32 v174, v48, v49
	v_cvt_pk_bf16_f32 v175, v50, v51
	v_cvt_pk_bf16_f32 v176, v52, v53
	v_mfma_f32_32x32x16_bf16 v[16:31], v[10:13], v[170:173], v[16:31]
	v_cvt_pk_bf16_f32 v177, v54, v55
	v_exp_f32_e32 v56, v56
	v_exp_f32_e32 v57, v57
	v_exp_f32_e32 v58, v58
	v_exp_f32_e32 v59, v59
	v_exp_f32_e32 v60, v60
	v_exp_f32_e32 v61, v61
	v_mfma_f32_32x32x16_bf16 v[32:47], v[136:139], v[174:177], v[32:47]
	v_exp_f32_e32 v62, v62
	v_exp_f32_e32 v63, v63
	v_cvt_pk_bf16_f32 v178, v56, v57
	v_cvt_pk_bf16_f32 v179, v58, v59
	v_cvt_pk_bf16_f32 v180, v60, v61
	v_cvt_pk_bf16_f32 v181, v62, v63
	s_waitcnt vmcnt(1)
	ds_write_b128 v157, v[116:119] offset:22528
	v_mfma_f32_32x32x16_bf16 v[16:31], v[2:5], v[174:177], v[16:31]
	v_mfma_f32_32x32x16_bf16 v[32:47], v[132:135], v[178:181], v[32:47]
	v_mfma_f32_32x32x16_bf16 v[16:31], v[6:9], v[178:181], v[16:31]
	s_and_saveexec_b64 s[12:13], s[38:39]
	ds_write_b128 v158, v[108:111] offset:22528
	s_or_b64 exec, exec, s[12:13]
	s_add_i32 s12, s22, 3
	s_cmp_ge_u32 s12, s14
	s_waitcnt vmcnt(0)
	ds_write_b128 v160, v[124:127] offset:35840
	s_waitcnt lgkmcnt(0)
	s_barrier
	s_barrier
	s_cbranch_scc1 .LBB0_174_sl
	v_add_co_u32_e32 v2, vcc, 0x9186000, v14
	s_nop 1
	v_addc_co_u32_e32 v3, vcc, 0, v15, vcc
	global_load_dwordx4 v[116:119], v[2:3], off offset:2048
	s_and_saveexec_b64 s[12:13], s[38:39]
	s_cbranch_execz .LBB0_173_sl
	v_lshl_add_u64 v[2:3], v[154:155], 0, s[20:21]
	v_add_co_u32_e32 v2, vcc, 0x9186000, v2
	s_nop 1
	v_addc_co_u32_e32 v3, vcc, 0, v3, vcc
	global_load_dwordx4 v[108:111], v[2:3], off offset:2048

.LBB0_180_sl:
	v_add_f32_e32 v2, 0, v14
	v_add_f32_e32 v3, 0, v15
	v_add_f32_e32 v2, v2, v48
	v_add_f32_e32 v3, v3, v49
	v_add_f32_e32 v2, v64, v2
	v_add_f32_e32 v3, v50, v3
	v_add_f32_e32 v2, v65, v2
	v_add_f32_e32 v3, v51, v3
	v_add_f32_e32 v2, v66, v2
	v_add_f32_e32 v3, v52, v3
	v_add_f32_e32 v2, v67, v2
	v_add_f32_e32 v3, v53, v3
	v_add_f32_e32 v2, v68, v2
	v_add_f32_e32 v3, v54, v3
	v_add_f32_e32 v2, v69, v2
	v_add_f32_e32 v3, v55, v3
	v_add_f32_e32 v2, v70, v2
	v_add_f32_e32 v3, v56, v3
	v_add_f32_e32 v2, v71, v2
	v_add_f32_e32 v3, v57, v3
	v_add_f32_e32 v2, v72, v2
	v_add_f32_e32 v3, v58, v3
	v_add_f32_e32 v2, v73, v2
	v_add_f32_e32 v3, v59, v3
	v_add_f32_e32 v2, v74, v2
	v_add_f32_e32 v3, v60, v3
	v_add_f32_e32 v2, v75, v2
	v_add_f32_e32 v3, v61, v3
	v_add_f32_e32 v2, v76, v2
	v_add_f32_e32 v3, v62, v3
	v_add_f32_e32 v2, v77, v2
	v_add_f32_e32 v3, v63, v3
	v_add_f32_e32 v2, v3, v2
	v_add_f32_e32 v0, v0, v2
	v_lshl_add_u64 v[150:151], v[150:151], 0, s[30:31]
	v_lshl_add_u64 v[152:153], v[152:153], 0, s[26:27]
	s_andn2_b64 vcc, exec, s[90:91]
	v_lshl_add_u64 v[154:155], v[154:155], 0, s[26:27]
	s_waitcnt lgkmcnt(0)
	s_barrier
	s_barrier
	s_cbranch_vccz .LBB0_203
	s_mov_b32 s22, s15
	s_branch .LBB0_162_sl

.LBB0_184:
	s_lshl_b32 s2, s64, 2
	s_add_i32 s2, s2, s33
	s_mul_i32 s40, s2, 0x108000
	s_mul_hi_i32 s41, s2, 0x108000
	s_add_u32 s12, s77, s40
	s_addc_u32 s13, s71, s41
	s_add_u32 s22, s72, s40
	v_ashrrev_i32_e32 v0, 31, v148
	s_addc_u32 s23, s66, s41
	v_lshrrev_b32_e32 v0, 29, v0
	s_add_u32 s14, s24, s40
	v_add_u32_e32 v0, v148, v0
	s_addc_u32 s15, s76, s41
	v_ashrrev_i32_e32 v26, 3, v0
	v_and_b32_e32 v0, -8, v0
	s_and_b64 s[2:3], s[88:89], exec
	v_sub_u32_e32 v27, v148, v0
	v_lshlrev_b32_e32 v0, 6, v26
	s_cselect_b32 s3, 0, 0x2000
	v_lshl_add_u32 v2, v27, 3, v0
	v_mov_b64_e32 v[4:5], s[14:15]
	v_lshlrev_b32_e32 v0, 4, v148
	s_cselect_b32 s2, 0x84, 4
	v_mad_i64_i32 v[4:5], s[14:15], v156, s54, v[4:5]
	v_and_b32_e32 v18, 0x70, v0
	v_mov_b32_e32 v19, v1
	s_lshl_b32 s38, s3, 7
	v_lshl_add_u64 v[4:5], v[4:5], 0, v[18:19]
	s_add_u32 s14, s22, s38
	v_ashrrev_i32_e32 v3, 31, v2
	v_lshrrev_b32_e32 v6, 1, v148
	v_and_b32_e32 v19, 31, v148
	s_addc_u32 s15, s23, 0
	v_lshlrev_b64 v[20:21], 1, v[2:3]
	v_and_or_b32 v0, v6, s5, v19
	v_lshl_add_u64 v[2:3], s[14:15], 0, v[20:21]
	s_lshl_b32 s96, s3, 1
	v_and_b32_e32 v22, 0xffffffe0, v156
	v_add_lshl_u32 v0, v0, s65, 7
	v_lshl_add_u64 v[4:5], v[4:5], 0, s[96:97]
	global_load_dwordx4 v[66:69], v[2:3], off
	global_load_dwordx4 v[78:81], v[4:5], off
	v_lshl_add_u64 v[2:3], s[12:13], 0, v[0:1]
	v_ashrrev_i32_e32 v23, 31, v22
	s_or_b32 s3, s38, 0x2000
	v_lshl_add_u64 v[2:3], v[22:23], 1, v[2:3]
	v_and_b32_e32 v0, 16, v6
	s_add_u32 s12, s22, s3
	v_lshl_add_u64 v[2:3], v[2:3], 0, v[0:1]
	s_addc_u32 s13, s23, 0
	global_load_dwordx4 v[70:73], v[2:3], off
	global_load_dwordx4 v[74:77], v[2:3], off offset:32
	v_lshl_add_u64 v[2:3], s[12:13], 0, v[20:21]
	global_load_dwordx4 v[86:89], v[4:5], off offset:128
	global_load_dwordx4 v[82:85], v[2:3], off
	v_mad_i64_i32 v[24:25], s[12:13], v156, s54, 0
	v_mad_u64_u32 v[122:123], s[12:13], v156, s4, v[18:19]
	s_add_u32 s12, s36, s96
	v_or_b32_e32 v24, v24, v18
	s_addc_u32 s13, s37, 0
	v_cmp_lt_i32_e32 vcc, v207, v206
	s_waitcnt vmcnt(14)
	v_lshl_add_u64 v[124:125], s[12:13], 0, v[24:25]
	s_add_u32 s12, s36, s38
	v_cndmask_b32_e32 v23, v205, v207, vcc
	v_mul_u32_u24_e32 v133, 0x90, v19
	v_mul_lo_u32 v18, v26, s4
	v_lshl_or_b32 v34, v22, 1, v0
	s_addc_u32 s13, s37, 0
	s_mov_b32 s3, 3
	v_mov_b32_e32 v2, v1
	v_mov_b32_e32 v3, v1
	v_mov_b32_e32 v4, v1
	v_mov_b32_e32 v5, v1
	v_mov_b32_e32 v6, v1
	v_mov_b32_e32 v7, v1
	v_mov_b32_e32 v8, v1
	v_mov_b32_e32 v9, v1
	v_mov_b32_e32 v10, v1
	v_mov_b32_e32 v11, v1
	v_mov_b32_e32 v12, v1
	v_mov_b32_e32 v13, v1
	v_mov_b32_e32 v14, v1
	v_mov_b32_e32 v15, v1
	v_mov_b32_e32 v16, v1
	v_mov_b32_e32 v17, v1
	v_lshlrev_b32_e32 v132, 2, v23
	v_lshl_add_u32 v123, v27, 4, v18
	v_lshl_add_u64 v[126:127], s[12:13], 0, v[20:21]
	v_mov_b32_e32 v18, v1
	v_mov_b32_e32 v19, v1
	v_mov_b32_e32 v20, v1
	v_mov_b32_e32 v21, v1
	v_mov_b32_e32 v22, v1
	v_mov_b32_e32 v23, v1
	v_mov_b32_e32 v24, v1
	v_mov_b32_e32 v25, v1
	v_mov_b32_e32 v26, v1
	v_mov_b32_e32 v27, v1
	v_mov_b32_e32 v28, v1
	v_mov_b32_e32 v29, v1
	v_mov_b32_e32 v30, v1
	v_mov_b32_e32 v31, v1
	v_mov_b32_e32 v32, v1
	v_mov_b32_e32 v33, v1
	v_mov_b32_e32 v134, 0
	v_bfrev_b32_e32 v218, 1
	v_mov_b32_e32 v219, v218
	v_mov_b32_e32 v220, v218
	v_mov_b32_e32 v221, v218
	v_mov_b32_e32 v222, v218
	v_mov_b32_e32 v223, v218
	v_mov_b32_e32 v224, v218
	v_mov_b32_e32 v225, v218
	v_mov_b32_e32 v226, v218
	v_mov_b32_e32 v227, v218
	v_mov_b32_e32 v228, v218
	v_mov_b32_e32 v229, v218
	v_mov_b32_e32 v230, v218
	v_mov_b32_e32 v231, v218
	v_mov_b32_e32 v232, v218
	v_mov_b32_e32 v233, v218
	v_add_u32_e32 v135, v133, v34
	v_mov_b32_e32 v136, 0
	s_waitcnt vmcnt(5)
	ds_write_b128 v123, v[66:69]
	s_waitcnt vmcnt(4)
	ds_write_b128 v122, v[78:81] offset:9216
	s_waitcnt lgkmcnt(0)
	s_barrier
	s_cmp_lg_u32 s98, 0
	s_cbranch_scc1 .LBB0_186_sl
	v_lshl_add_u64 v[238:239], v[126:127], 0, s[40:41]
	v_lshl_add_u64 v[242:243], v[124:125], 0, s[40:41]
	s_mov_b32 s12, 0x6e73800
	s_mov_b32 s13, 0
	v_lshl_add_u64 v[240:241], v[238:239], 0, s[12:13]
	s_mov_b32 s12, 0x6e71800
	v_lshl_add_u64 v[238:239], v[238:239], 0, s[12:13]
	s_mov_b32 s12, 0x76ad900
	v_lshl_add_u64 v[242:243], v[242:243], 0, s[12:13]
	s_branch .LBB0_186
.LBB0_185:
	v_add_f32_e32 v50, 0, v50
	v_add_f32_e32 v34, 0, v34
	v_add_f32_e32 v50, v50, v51
	v_add_f32_e32 v34, v34, v35
	v_add_f32_e32 v35, v52, v50
	v_add_f32_e32 v34, v36, v34
	v_add_f32_e32 v35, v53, v35
	v_add_f32_e32 v34, v37, v34
	v_add_f32_e32 v35, v54, v35
	v_add_f32_e32 v34, v38, v34
	v_add_f32_e32 v35, v55, v35
	v_add_f32_e32 v34, v39, v34
	v_add_f32_e32 v35, v56, v35
	v_add_f32_e32 v34, v40, v34
	v_add_f32_e32 v35, v57, v35
	v_add_f32_e32 v34, v41, v34
	v_add_f32_e32 v35, v58, v35
	v_add_f32_e32 v34, v42, v34
	v_add_f32_e32 v35, v59, v35
	v_add_f32_e32 v34, v43, v34
	v_add_f32_e32 v35, v60, v35
	v_add_f32_e32 v34, v44, v34
	v_add_f32_e32 v35, v61, v35
	v_add_f32_e32 v34, v45, v34
	v_add_f32_e32 v35, v62, v35
	v_add_f32_e32 v34, v46, v34
	v_add_f32_e32 v35, v63, v35
	v_add_f32_e32 v34, v47, v34
	v_add_f32_e32 v35, v64, v35
	v_add_f32_e32 v34, v48, v34
	v_add_f32_e32 v35, v65, v35
	v_add_f32_e32 v34, v49, v34
	v_add_f32_e32 v34, v34, v35
	s_add_i32 s3, s3, 2
	v_add_f32_e32 v136, v128, v34
	v_lshl_add_u64 v[242:243], v[242:243], 0, s[30:31]
	s_cmp_lt_u32 s12, s2
	v_lshl_add_u64 v[238:239], v[238:239], 0, s[28:29]
	v_lshl_add_u64 v[240:241], v[240:241], 0, s[28:29]
	s_waitcnt lgkmcnt(0)
	s_barrier
	s_barrier
	s_cbranch_scc0 .LBB0_196
.LBB0_186:
	s_add_i32 s12, s3, -1
	s_cmp_lt_u32 s12, s2
	s_cselect_b64 s[88:89], -1, 0
	s_cmp_ge_u32 s12, s2
	s_cbranch_scc1 .LBB0_188
	global_load_dwordx4 v[66:69], v[238:239], off
	global_load_dwordx4 v[78:81], v[242:243], off

.LBB0_190:
	v_exp_f32_e32 v50, v50
	v_exp_f32_e32 v51, v51
	v_exp_f32_e32 v52, v52
	v_exp_f32_e32 v53, v53
	v_exp_f32_e32 v54, v54
	v_exp_f32_e32 v55, v55
	v_exp_f32_e32 v56, v56
	v_exp_f32_e32 v57, v57
	v_cvt_pk_bf16_f32 v138, v50, v51
	v_cvt_pk_bf16_f32 v139, v52, v53
	v_cvt_pk_bf16_f32 v140, v54, v55
	v_cvt_pk_bf16_f32 v141, v56, v57
	v_exp_f32_e32 v58, v58
	v_exp_f32_e32 v59, v59
	s_waitcnt lgkmcnt(0)
	v_mfma_f32_32x32x16_bf16 v[2:17], v[118:121], v[138:141], v[2:17]
	v_exp_f32_e32 v60, v60
	v_exp_f32_e32 v61, v61
	v_exp_f32_e32 v62, v62
	v_exp_f32_e32 v63, v63
	v_exp_f32_e32 v64, v64
	v_exp_f32_e32 v65, v65
	v_cvt_pk_bf16_f32 v142, v58, v59
	v_mfma_f32_32x32x16_bf16 v[18:33], v[102:105], v[138:141], v[18:33]
	v_cvt_pk_bf16_f32 v143, v60, v61
	v_cvt_pk_bf16_f32 v144, v62, v63
	v_cvt_pk_bf16_f32 v145, v64, v65
	v_exp_f32_e32 v34, v34
	v_exp_f32_e32 v35, v35
	v_exp_f32_e32 v36, v36
	v_exp_f32_e32 v37, v37
	v_mfma_f32_32x32x16_bf16 v[2:17], v[114:117], v[142:145], v[2:17]
	v_exp_f32_e32 v38, v38
	v_exp_f32_e32 v39, v39
	v_exp_f32_e32 v40, v40
	v_exp_f32_e32 v41, v41
	v_cvt_pk_bf16_f32 v150, v34, v35
	v_cvt_pk_bf16_f32 v151, v36, v37
	v_cvt_pk_bf16_f32 v152, v38, v39
	v_mfma_f32_32x32x16_bf16 v[18:33], v[98:101], v[142:145], v[18:33]
	v_cvt_pk_bf16_f32 v153, v40, v41
	v_exp_f32_e32 v42, v42
	v_exp_f32_e32 v43, v43
	v_exp_f32_e32 v44, v44
	v_exp_f32_e32 v45, v45
	v_exp_f32_e32 v46, v46
	v_exp_f32_e32 v47, v47
	v_mfma_f32_32x32x16_bf16 v[2:17], v[110:113], v[150:153], v[2:17]
	v_exp_f32_e32 v48, v48
	v_exp_f32_e32 v49, v49
	v_cvt_pk_bf16_f32 v154, v42, v43
	v_cvt_pk_bf16_f32 v155, v44, v45
	v_cvt_pk_bf16_f32 v156, v46, v47
	v_cvt_pk_bf16_f32 v157, v48, v49
	s_cmp_ge_u32 s3, s2
	v_mfma_f32_32x32x16_bf16 v[18:33], v[90:93], v[150:153], v[18:33]
	s_waitcnt vmcnt(0)
	ds_write_b128 v123, v[82:85] offset:18432
	ds_write_b128 v122, v[86:89] offset:27648
	s_waitcnt lgkmcnt(0)
	s_barrier
	s_barrier
	v_mfma_f32_32x32x16_bf16 v[2:17], v[106:109], v[154:157], v[2:17]
	v_mfma_f32_32x32x16_bf16 v[18:33], v[94:97], v[154:157], v[18:33]
	s_cbranch_scc1 .LBB0_192
	global_load_dwordx4 v[82:85], v[240:241], off
	global_load_dwordx4 v[86:89], v[242:243], off offset:128

.LBB0_185_sl:
	v_add_f32_e32 v50, 0, v50
	v_add_f32_e32 v34, 0, v34
	v_add_f32_e32 v50, v50, v51
	v_add_f32_e32 v34, v34, v35
	v_add_f32_e32 v35, v52, v50
	v_add_f32_e32 v34, v36, v34
	v_add_f32_e32 v35, v53, v35
	v_add_f32_e32 v34, v37, v34
	v_add_f32_e32 v35, v54, v35
	v_add_f32_e32 v34, v38, v34
	v_add_f32_e32 v35, v55, v35
	v_add_f32_e32 v34, v39, v34
	v_add_f32_e32 v35, v56, v35
	v_add_f32_e32 v34, v40, v34
	v_add_f32_e32 v35, v57, v35
	v_add_f32_e32 v34, v41, v34
	v_add_f32_e32 v35, v58, v35
	v_add_f32_e32 v34, v42, v34
	v_add_f32_e32 v35, v59, v35
	v_add_f32_e32 v34, v43, v34
	v_add_f32_e32 v35, v60, v35
	v_add_f32_e32 v34, v44, v34
	v_add_f32_e32 v35, v61, v35
	v_add_f32_e32 v34, v45, v34
	v_add_f32_e32 v35, v62, v35
	v_add_f32_e32 v34, v46, v34
	v_add_f32_e32 v35, v63, v35
	v_add_f32_e32 v34, v47, v34
	v_add_f32_e32 v35, v64, v35
	v_add_f32_e32 v34, v48, v34
	v_add_f32_e32 v35, v65, v35
	v_add_f32_e32 v34, v49, v34
	v_add_f32_e32 v34, v34, v35
	s_add_i32 s3, s3, 2
	v_add_f32_e32 v136, v128, v34
	v_lshl_add_u64 v[124:125], v[124:125], 0, s[30:31]
	s_cmp_lt_u32 s12, s2
	v_lshl_add_u64 v[126:127], v[126:127], 0, s[28:29]
	s_waitcnt lgkmcnt(0)
	s_barrier
	s_barrier
	s_cbranch_scc0 .LBB0_196

.LBB0_190_sl:
	v_exp_f32_e32 v50, v50
	v_exp_f32_e32 v51, v51
	v_exp_f32_e32 v52, v52
	v_exp_f32_e32 v53, v53
	v_exp_f32_e32 v54, v54
	v_exp_f32_e32 v55, v55
	v_exp_f32_e32 v56, v56
	v_exp_f32_e32 v57, v57
	v_cvt_pk_bf16_f32 v138, v50, v51
	v_cvt_pk_bf16_f32 v139, v52, v53
	v_cvt_pk_bf16_f32 v140, v54, v55
	v_cvt_pk_bf16_f32 v141, v56, v57
	v_exp_f32_e32 v58, v58
	v_exp_f32_e32 v59, v59
	s_waitcnt lgkmcnt(0)
	v_mfma_f32_32x32x16_bf16 v[2:17], v[118:121], v[138:141], v[2:17]
	v_exp_f32_e32 v60, v60
	v_exp_f32_e32 v61, v61
	v_exp_f32_e32 v62, v62
	v_exp_f32_e32 v63, v63
	v_exp_f32_e32 v64, v64
	v_exp_f32_e32 v65, v65
	v_cvt_pk_bf16_f32 v142, v58, v59
	v_mfma_f32_32x32x16_bf16 v[18:33], v[102:105], v[138:141], v[18:33]
	v_cvt_pk_bf16_f32 v143, v60, v61
	v_cvt_pk_bf16_f32 v144, v62, v63
	v_cvt_pk_bf16_f32 v145, v64, v65
	v_exp_f32_e32 v34, v34
	v_exp_f32_e32 v35, v35
	v_exp_f32_e32 v36, v36
	v_exp_f32_e32 v37, v37
	v_mfma_f32_32x32x16_bf16 v[2:17], v[114:117], v[142:145], v[2:17]
	v_exp_f32_e32 v38, v38
	v_exp_f32_e32 v39, v39
	v_exp_f32_e32 v40, v40
	v_exp_f32_e32 v41, v41
	v_cvt_pk_bf16_f32 v150, v34, v35
	v_cvt_pk_bf16_f32 v151, v36, v37
	v_cvt_pk_bf16_f32 v152, v38, v39
	v_mfma_f32_32x32x16_bf16 v[18:33], v[98:101], v[142:145], v[18:33]
	v_cvt_pk_bf16_f32 v153, v40, v41
	v_exp_f32_e32 v42, v42
	v_exp_f32_e32 v43, v43
	v_exp_f32_e32 v44, v44
	v_exp_f32_e32 v45, v45
	v_exp_f32_e32 v46, v46
	v_exp_f32_e32 v47, v47
	v_mfma_f32_32x32x16_bf16 v[2:17], v[110:113], v[150:153], v[2:17]
	v_exp_f32_e32 v48, v48
	v_exp_f32_e32 v49, v49
	v_cvt_pk_bf16_f32 v154, v42, v43
	v_cvt_pk_bf16_f32 v155, v44, v45
	v_cvt_pk_bf16_f32 v156, v46, v47
	v_cvt_pk_bf16_f32 v157, v48, v49
	s_cmp_ge_u32 s3, s2
	v_mfma_f32_32x32x16_bf16 v[18:33], v[90:93], v[150:153], v[18:33]
	s_waitcnt vmcnt(0)
	ds_write_b128 v123, v[82:85] offset:18432
	ds_write_b128 v122, v[86:89] offset:27648
	s_waitcnt lgkmcnt(0)
	s_barrier
	s_barrier
	v_mfma_f32_32x32x16_bf16 v[2:17], v[106:109], v[154:157], v[2:17]
	v_mfma_f32_32x32x16_bf16 v[18:33], v[94:97], v[154:157], v[18:33]
	s_cbranch_scc1 .LBB0_192_sl
	v_add_co_u32_e32 v82, vcc, 0x6e73000, v130
	s_nop 1
	v_addc_co_u32_e32 v83, vcc, 0, v131, vcc
	v_add_co_u32_e32 v86, vcc, 0x76ad000, v128
	global_load_dwordx4 v[82:85], v[82:83], off offset:2048
	s_nop 0
	v_addc_co_u32_e32 v87, vcc, 0, v129, vcc
	global_load_dwordx4 v[86:89], v[86:87], off offset:2432
